# grid barrier: non-leader workgroups spin on the global generation word with a local barrier index (one hand-off hop less)
# baseline (speedup 1.0000x reference)
_Z10fwd_kernel6Params:
	s_load_dwordx8 s[80:87], s[0:1], 0x80
	s_add_u32 s4, s0, 0x98
	s_mov_b32 s68, s2
	s_addc_u32 s5, s1, 0
	v_and_b32_e32 v160, 0x3ff, v0
	v_writelane_b32 v242, 0, 27
	s_waitcnt lgkmcnt(0)
	s_and_b32 s2, s86, 7
	v_readfirstlane_b32 s10, v160
	s_cmp_lg_u32 s2, 0
	s_mov_b32 s45, s68
	s_cbranch_scc1 .LBB0_2
	s_ashr_i32 s3, s68, 31
	s_lshr_b32 s3, s3, 29
	s_add_i32 s3, s68, s3
	s_ashr_i32 s6, s3, 3
	s_and_b32 s3, s3, -8
	s_ashr_i32 s2, s86, 3
	s_sub_i32 s3, s68, s3
	s_mul_i32 s2, s2, s3
	s_add_i32 s45, s2, s6

.LBB0_440:
	s_waitcnt vmcnt(0)
	s_barrier
	s_mov_b64 s[0:1], exec
	v_readlane_b32 s2, v247, 0
	v_readlane_b32 s3, v247, 1
	v_readlane_b32 s78, v242, 1
	s_and_b64 s[2:3], s[0:1], s[2:3]
	v_readlane_b32 s79, v242, 2
	s_mov_b64 exec, s[2:3]
	s_cbranch_execz .LBB0_492
	v_readlane_b32 s2, v242, 27
	s_nop 3
	s_add_u32 s2, s2, 1
	s_nop 0
	v_writelane_b32 v242, s2, 27
	v_readlane_b32 s2, v243, 47
	s_waitcnt vmcnt(0) expcnt(0) lgkmcnt(0)
	s_nop 0
	v_mov_b32_e32 v0, s2
	ds_read_b32 v2, v0
	v_readlane_b32 s2, v243, 48
	s_waitcnt lgkmcnt(0)
	v_cmp_ne_u32_e32 vcc, 0, v2
	v_mov_b32_e32 v0, s2
	ds_read_b32 v0, v0
	s_cbranch_vccnz .LBB0_456
	s_mov_b32 s4, 1
	s_branch .LBB0_444

.LBB0_458:
	s_or_b64 exec, exec, s[2:3]
	v_cvt_f32_u32_e32 v4, v2
	s_waitcnt vmcnt(0)
	v_readfirstlane_b32 s2, v3
	v_sub_u32_e32 v3, 0, v2
	v_rcp_iflag_f32_e32 v4, v4
	v_add_u32_e32 v5, s2, v1
	v_mul_f32_e32 v4, 0x4f7ffffe, v4
	v_cvt_u32_f32_e32 v4, v4
	v_mul_lo_u32 v1, v3, v4
	v_mul_hi_u32 v1, v4, v1
	v_add_u32_e32 v1, v4, v1
	v_mul_hi_u32 v1, v5, v1
	v_mul_lo_u32 v3, v1, v2
	v_sub_u32_e32 v3, v5, v3
	v_add_u32_e32 v4, 1, v1
	v_cmp_ge_u32_e32 vcc, v3, v2
	s_nop 1
	v_cndmask_b32_e32 v1, v1, v4, vcc
	v_sub_u32_e32 v4, v3, v2
	v_cndmask_b32_e32 v3, v3, v4, vcc
	v_add_u32_e32 v4, 1, v1
	v_cmp_ge_u32_e32 vcc, v3, v2
	v_add_u32_e32 v3, 1, v5
	s_nop 0
	v_cndmask_b32_e32 v1, v1, v4, vcc
	v_mul_lo_u32 v4, v2, v1
	v_add_u32_e32 v2, v4, v2
	v_cmp_ne_u32_e32 vcc, v3, v2
	s_and_saveexec_b64 s[2:3], vcc
	s_xor_b64 s[2:3], exec, s[2:3]
	s_cbranch_execz .LBB0_472
	v_readlane_b32 s4, v246, 57
	v_readlane_b32 s5, v246, 58
	v_readlane_b32 s6, v242, 27
	s_waitcnt lgkmcnt(0)
	s_nop 3
	s_sub_u32 s6, s6, 1
	s_nop 0
	v_mov_b32_e32 v1, s6
	global_load_dword v0, v163, s[4:5] sc1
	s_waitcnt vmcnt(0)
	v_cmp_eq_u32_e32 vcc, v0, v1
	s_and_saveexec_b64 s[36:37], vcc
	s_cbranch_execz .LBB0_471
	s_mov_b32 s4, 1
	s_mov_b64 s[38:39], 0
	s_branch .LBB0_462

.LBB0_464:
	v_readlane_b32 s6, v246, 57
	v_readlane_b32 s7, v246, 58
	s_add_i32 s4, s4, 1
	s_mov_b64 s[48:49], -1
	s_nop 2
	global_load_dword v0, v163, s[6:7] sc1
	s_waitcnt vmcnt(0)
	v_cmp_ne_u32_e32 vcc, v0, v1
	s_orn2_b64 s[42:43], vcc, exec
	s_branch .LBB0_461

.LBB0_516:
	s_waitcnt vmcnt(0)
	s_barrier
	s_mov_b64 s[0:1], exec
	v_readlane_b32 s2, v247, 0
	v_readlane_b32 s3, v247, 1
	s_and_b64 s[2:3], s[0:1], s[2:3]
	s_mov_b64 exec, s[2:3]
	s_cbranch_execz .LBB0_568
	v_readlane_b32 s2, v242, 27
	s_nop 3
	s_add_u32 s2, s2, 1
	s_nop 0
	v_writelane_b32 v242, s2, 27
	v_readlane_b32 s2, v243, 47
	s_waitcnt vmcnt(0) expcnt(0) lgkmcnt(0)
	s_nop 0
	v_mov_b32_e32 v0, s2
	ds_read_b32 v2, v0
	v_readlane_b32 s2, v243, 48
	s_waitcnt lgkmcnt(0)
	v_cmp_ne_u32_e32 vcc, 0, v2
	v_mov_b32_e32 v0, s2
	ds_read_b32 v0, v0
	s_cbranch_vccnz .LBB0_532
	s_mov_b32 s4, 1
	s_branch .LBB0_520

.LBB0_589:
	s_waitcnt vmcnt(0)
	s_barrier
	s_mov_b64 s[0:1], exec
	v_readlane_b32 s2, v247, 0
	v_readlane_b32 s3, v247, 1
	v_readlane_b32 s24, v247, 49
	s_and_b64 s[2:3], s[0:1], s[2:3]
	v_readlane_b32 s25, v247, 50
	s_mov_b64 exec, s[2:3]
	s_cbranch_execz .LBB0_641
	v_readlane_b32 s2, v242, 27
	s_nop 3
	s_add_u32 s2, s2, 1
	s_nop 0
	v_writelane_b32 v242, s2, 27
	v_readlane_b32 s2, v243, 47
	s_waitcnt vmcnt(0) expcnt(0) lgkmcnt(0)
	s_nop 0
	v_mov_b32_e32 v0, s2
	ds_read_b32 v2, v0
	v_readlane_b32 s2, v243, 48
	s_waitcnt lgkmcnt(0)
	v_cmp_ne_u32_e32 vcc, 0, v2
	v_mov_b32_e32 v0, s2
	ds_read_b32 v0, v0
	s_cbranch_vccnz .LBB0_605
	s_mov_b32 s4, 1
	s_branch .LBB0_593

.LBB0_607:
	s_or_b64 exec, exec, s[2:3]
	v_cvt_f32_u32_e32 v4, v2
	s_waitcnt vmcnt(0)
	v_readfirstlane_b32 s2, v3
	v_sub_u32_e32 v3, 0, v2
	v_rcp_iflag_f32_e32 v4, v4
	v_add_u32_e32 v5, s2, v1
	v_mul_f32_e32 v4, 0x4f7ffffe, v4
	v_cvt_u32_f32_e32 v4, v4
	v_mul_lo_u32 v1, v3, v4
	v_mul_hi_u32 v1, v4, v1
	v_add_u32_e32 v1, v4, v1
	v_mul_hi_u32 v1, v5, v1
	v_mul_lo_u32 v3, v1, v2
	v_sub_u32_e32 v3, v5, v3
	v_add_u32_e32 v4, 1, v1
	v_sub_u32_e32 v6, v3, v2
	v_cmp_ge_u32_e32 vcc, v3, v2
	s_nop 1
	v_cndmask_b32_e32 v1, v1, v4, vcc
	v_cndmask_b32_e32 v3, v3, v6, vcc
	v_add_u32_e32 v4, 1, v1
	v_cmp_ge_u32_e32 vcc, v3, v2
	v_add_u32_e32 v3, 1, v5
	s_nop 0
	v_cndmask_b32_e32 v1, v1, v4, vcc
	v_mul_lo_u32 v4, v2, v1
	v_add_u32_e32 v2, v4, v2
	v_cmp_ne_u32_e32 vcc, v3, v2
	s_and_saveexec_b64 s[2:3], vcc
	s_xor_b64 s[2:3], exec, s[2:3]
	s_cbranch_execz .LBB0_621
	v_readlane_b32 s4, v246, 57
	v_readlane_b32 s5, v246, 58
	v_readlane_b32 s6, v242, 27
	s_waitcnt lgkmcnt(0)
	s_nop 3
	s_sub_u32 s6, s6, 1
	s_nop 0
	v_mov_b32_e32 v1, s6
	global_load_dword v0, v163, s[4:5] sc1
	s_waitcnt vmcnt(0)
	v_cmp_eq_u32_e32 vcc, v0, v1
	s_and_saveexec_b64 s[36:37], vcc
	s_cbranch_execz .LBB0_620
	s_mov_b32 s4, 1
	s_mov_b64 s[38:39], 0
	s_branch .LBB0_611

.LBB0_711:
	s_waitcnt vmcnt(0)
	s_waitcnt vmcnt(0)
	s_barrier
	s_mov_b64 s[2:3], exec
	v_readlane_b32 s4, v247, 0
	v_readlane_b32 s5, v247, 1
	s_and_b64 s[4:5], s[2:3], s[4:5]
	s_mov_b64 exec, s[4:5]
	s_cbranch_execz .LBB0_763
	v_readlane_b32 s4, v242, 27
	s_nop 3
	s_add_u32 s4, s4, 1
	s_nop 0
	v_writelane_b32 v242, s4, 27
	v_readlane_b32 s4, v243, 47
	s_waitcnt vmcnt(0) expcnt(0) lgkmcnt(0)
	s_nop 0
	v_mov_b32_e32 v0, s4
	ds_read_b32 v2, v0
	v_readlane_b32 s4, v243, 48
	s_waitcnt lgkmcnt(0)
	v_cmp_ne_u32_e32 vcc, 0, v2
	v_mov_b32_e32 v0, s4
	ds_read_b32 v0, v0
	s_cbranch_vccnz .LBB0_727
	s_mov_b32 s4, 1
	s_branch .LBB0_715

.LBB0_729:
	s_or_b64 exec, exec, s[36:37]
	v_cvt_f32_u32_e32 v4, v2
	s_waitcnt vmcnt(0)
	v_readfirstlane_b32 s4, v3
	v_sub_u32_e32 v3, 0, v2
	v_rcp_iflag_f32_e32 v4, v4
	v_add_u32_e32 v5, s4, v1
	v_mul_f32_e32 v4, 0x4f7ffffe, v4
	v_cvt_u32_f32_e32 v4, v4
	v_mul_lo_u32 v1, v3, v4
	v_mul_hi_u32 v1, v4, v1
	v_add_u32_e32 v1, v4, v1
	v_mul_hi_u32 v1, v5, v1
	v_mul_lo_u32 v3, v1, v2
	v_sub_u32_e32 v3, v5, v3
	v_add_u32_e32 v4, 1, v1
	v_cmp_ge_u32_e32 vcc, v3, v2
	s_nop 1
	v_cndmask_b32_e32 v1, v1, v4, vcc
	v_sub_u32_e32 v4, v3, v2
	v_cndmask_b32_e32 v3, v3, v4, vcc
	v_add_u32_e32 v4, 1, v1
	v_cmp_ge_u32_e32 vcc, v3, v2
	v_add_u32_e32 v3, 1, v5
	s_nop 0
	v_cndmask_b32_e32 v1, v1, v4, vcc
	v_mul_lo_u32 v4, v2, v1
	v_add_u32_e32 v2, v4, v2
	v_cmp_ne_u32_e32 vcc, v3, v2
	s_and_saveexec_b64 s[4:5], vcc
	s_xor_b64 s[36:37], exec, s[4:5]
	s_cbranch_execz .LBB0_743
	v_readlane_b32 s4, v246, 57
	v_readlane_b32 s5, v246, 58
	v_readlane_b32 s6, v242, 27
	s_waitcnt lgkmcnt(0)
	s_nop 3
	s_sub_u32 s6, s6, 1
	s_nop 0
	v_mov_b32_e32 v1, s6
	global_load_dword v0, v163, s[4:5] sc1
	s_waitcnt vmcnt(0)
	v_cmp_eq_u32_e32 vcc, v0, v1
	s_and_saveexec_b64 s[38:39], vcc
	s_cbranch_execz .LBB0_742
	s_mov_b32 s4, 1
	s_mov_b64 s[40:41], 0
	s_branch .LBB0_733

.LBB0_735:
	v_readlane_b32 s6, v246, 57
	v_readlane_b32 s7, v246, 58
	s_add_i32 s4, s4, 1
	s_mov_b64 s[50:51], -1
	s_nop 2
	global_load_dword v0, v163, s[6:7] sc1
	s_waitcnt vmcnt(0)
	v_cmp_ne_u32_e32 vcc, v0, v1
	s_orn2_b64 s[48:49], vcc, exec
	s_branch .LBB0_732

.LBB0_828:
	v_readlane_b32 s20, v242, 21
	v_readlane_b32 s21, v242, 22
	v_readlane_b32 s22, v242, 23
	v_readlane_b32 s23, v242, 24
	v_readlane_b32 s24, v242, 25
	v_readlane_b32 s25, v242, 26
	s_waitcnt vmcnt(0)
	s_waitcnt vmcnt(0) lgkmcnt(0)
	s_barrier
	s_mov_b64 s[2:3], exec
	v_readlane_b32 s4, v247, 0
	v_readlane_b32 s5, v247, 1
	v_readlane_b32 s6, v242, 3
	s_and_b64 s[4:5], s[2:3], s[4:5]
	v_readlane_b32 s7, v242, 4
	s_mov_b64 exec, s[4:5]
	s_cbranch_execz .LBB0_880
	v_readlane_b32 s4, v242, 27
	s_nop 3
	s_add_u32 s4, s4, 1
	s_nop 0
	v_writelane_b32 v242, s4, 27
	v_readlane_b32 s4, v243, 47
	s_waitcnt vmcnt(0) expcnt(0) lgkmcnt(0)
	s_nop 0
	v_mov_b32_e32 v0, s4
	ds_read_b32 v2, v0
	v_readlane_b32 s4, v243, 48
	s_waitcnt lgkmcnt(0)
	v_cmp_ne_u32_e32 vcc, 0, v2
	v_mov_b32_e32 v0, s4
	ds_read_b32 v0, v0
	s_cbranch_vccnz .LBB0_844
	s_mov_b32 s4, 1
	s_branch .LBB0_832

.LBB0_921:
	s_waitcnt vmcnt(0)
	s_waitcnt vmcnt(0)
	s_barrier
	s_mov_b64 s[2:3], exec
	v_readlane_b32 s4, v247, 0
	v_readlane_b32 s5, v247, 1
	v_readlane_b32 s10, v242, 3
	s_and_b64 s[4:5], s[2:3], s[4:5]
	v_readlane_b32 s11, v242, 4
	s_mov_b64 exec, s[4:5]
	s_cbranch_execz .LBB0_973
	v_readlane_b32 s4, v242, 27
	s_nop 3
	s_add_u32 s4, s4, 1
	s_nop 0
	v_writelane_b32 v242, s4, 27
	v_readlane_b32 s4, v243, 47
	s_waitcnt vmcnt(0) expcnt(0) lgkmcnt(0)
	s_nop 0
	v_mov_b32_e32 v0, s4
	ds_read_b32 v2, v0
	v_readlane_b32 s4, v243, 48
	s_waitcnt lgkmcnt(0)
	v_cmp_ne_u32_e32 vcc, 0, v2
	v_mov_b32_e32 v0, s4
	ds_read_b32 v0, v0
	s_cbranch_vccnz .LBB0_937
	s_mov_b32 s4, 1
	s_branch .LBB0_925

.LBB0_1016:
	s_waitcnt vmcnt(0)
	s_barrier
	s_mov_b64 s[0:1], exec
	v_readlane_b32 s2, v247, 0
	v_readlane_b32 s3, v247, 1
	v_readlane_b32 s24, v243, 61
	s_and_b64 s[2:3], s[0:1], s[2:3]
	v_readlane_b32 s25, v243, 62
	s_mov_b64 exec, s[2:3]
	s_cbranch_execz .LBB0_1068
	v_readlane_b32 s2, v242, 27
	s_nop 3
	s_add_u32 s2, s2, 1
	s_nop 0
	v_writelane_b32 v242, s2, 27
	v_readlane_b32 s2, v243, 47
	s_waitcnt vmcnt(0) expcnt(0) lgkmcnt(0)
	s_nop 0
	v_mov_b32_e32 v0, s2
	ds_read_b32 v2, v0
	v_readlane_b32 s2, v243, 48
	s_waitcnt lgkmcnt(0)
	v_cmp_ne_u32_e32 vcc, 0, v2
	v_mov_b32_e32 v0, s2
	ds_read_b32 v0, v0
	s_cbranch_vccnz .LBB0_1032
	s_mov_b32 s4, 1
	s_branch .LBB0_1020

.LBB0_1145:
	s_waitcnt vmcnt(0)
	s_waitcnt vmcnt(0)
	s_barrier
	s_mov_b64 s[0:1], exec
	v_readlane_b32 s2, v247, 0
	v_readlane_b32 s3, v247, 1
	s_and_b64 s[2:3], s[0:1], s[2:3]
	s_mov_b64 exec, s[2:3]
	s_cbranch_execz .LBB0_1197
	v_readlane_b32 s2, v242, 27
	s_nop 3
	s_add_u32 s2, s2, 1
	s_nop 0
	v_writelane_b32 v242, s2, 27
	v_readlane_b32 s2, v243, 47
	s_waitcnt vmcnt(0) expcnt(0) lgkmcnt(0)
	s_nop 0
	v_mov_b32_e32 v0, s2
	ds_read_b32 v2, v0
	v_readlane_b32 s2, v243, 48
	s_waitcnt lgkmcnt(0)
	v_cmp_ne_u32_e32 vcc, 0, v2
	v_mov_b32_e32 v0, s2
	ds_read_b32 v0, v0
	s_cbranch_vccnz .LBB0_1161
	s_mov_b32 s4, 1
	s_branch .LBB0_1149

.LBB0_1255:
	v_readlane_b32 s0, v242, 9
	s_cmp_lg_u32 s0, 0
	v_readlane_b32 s1, v242, 10
	s_cbranch_scc1 .LBB0_1311
	s_waitcnt vmcnt(0)
	s_waitcnt vmcnt(0)
	s_barrier
	s_mov_b64 s[0:1], exec
	v_readlane_b32 s2, v247, 0
	v_readlane_b32 s3, v247, 1
	s_and_b64 s[2:3], s[0:1], s[2:3]
	s_mov_b64 exec, s[2:3]
	s_cbranch_execz .LBB0_1308
	v_readlane_b32 s2, v242, 27
	s_nop 3
	s_add_u32 s2, s2, 1
	s_nop 0
	v_writelane_b32 v242, s2, 27
	v_readlane_b32 s2, v243, 47
	s_waitcnt vmcnt(0) expcnt(0) lgkmcnt(0)
	s_nop 0
	v_mov_b32_e32 v0, s2
	ds_read_b32 v2, v0
	v_readlane_b32 s2, v243, 48
	s_waitcnt lgkmcnt(0)
	v_cmp_ne_u32_e32 vcc, 0, v2
	v_mov_b32_e32 v0, s2
	ds_read_b32 v0, v0
	s_cbranch_vccnz .LBB0_1272
	s_mov_b32 s4, 1
	s_branch .LBB0_1260

.LBB0_1312:
	v_readlane_b32 s2, v242, 27
	s_nop 3
	s_add_u32 s2, s2, 1
	s_nop 0
	v_writelane_b32 v242, s2, 27
	v_readlane_b32 s2, v243, 47
	s_waitcnt vmcnt(0) expcnt(0) lgkmcnt(0)
	s_nop 0
	v_mov_b32_e32 v0, s2
	ds_read_b32 v2, v0
	v_readlane_b32 s2, v243, 48
	s_waitcnt lgkmcnt(0)
	v_cmp_ne_u32_e32 vcc, 0, v2
	v_mov_b32_e32 v0, s2
	ds_read_b32 v0, v0
	s_cbranch_vccnz .LBB0_1327
	s_mov_b32 s4, 1
	s_branch .LBB0_1315
